# GEMM tile loops: accumulators zeroed once per tile (hipcc's second, redundant 128-move zeroing block in the K-loop preheader removed)
# speedup vs baseline: 1.0051x; 1.0051x over previous
; template <class Epi>
; __device__ __forceinline__ void gemm_phase(LAS unsigned char* lds, const Gemm g, const StaticOrder& S, const Epi& E) {
;     ...
;     f32x4 acc[2][2][4][2];
; #pragma unroll
;     for (int a = 0; a < 2; ++a)
; #pragma unroll
;         for (int b = 0; b < 2; ++b)
; #pragma unroll
;             for (int m = 0; m < 4; ++m)
; #pragma unroll
;                 for (int n = 0; n < 2; ++n) acc[a][b][m][n] = (f32x4){0.f, 0.f, 0.f, 0.f};
;     ...
;     for (;;) {
;         const bool has_next = S.next(ui + 1, nxt);
;         const char* nA = has_next ? (const char*)g.A + (size_t)nxt.pm * tstep : cA; const char* nB = has_next ? (const char*)g.Bt + (size_t)nxt.pn * tstep : cB;
;         for (int t = 0; t < nt; t += 2) {
;             const bool last = (t == nt - 2);
;             const char* a1 = cA + (size_t)(t + 1) * kstep;
;             const char* a2 = last ? nA : cA + (size_t)(t + 2) * kstep; const char* b2 = last ? nB : cB + (size_t)(t + 2) * kstep;
;             const char* a3 = a2 + kstep; const char* b3 = b2 + kstep;
.LBB0_117:
	v_mov_b32_e32 v127, 0
	s_andn2_b64 vcc, exec, s[6:7]
	v_mov_b32_e32 v126, v127
	v_mov_b32_e32 v125, v127
	v_mov_b32_e32 v124, v127
	v_mov_b32_e32 v123, v127
	v_mov_b32_e32 v122, v127
	v_mov_b32_e32 v121, v127
	v_mov_b32_e32 v120, v127
	v_mov_b32_e32 v111, v127
	v_mov_b32_e32 v110, v127
	v_mov_b32_e32 v109, v127
	v_mov_b32_e32 v108, v127
	v_mov_b32_e32 v107, v127
	v_mov_b32_e32 v106, v127
	v_mov_b32_e32 v105, v127
	v_mov_b32_e32 v104, v127
	v_mov_b32_e32 v95, v127
	v_mov_b32_e32 v94, v127
	v_mov_b32_e32 v93, v127
	v_mov_b32_e32 v92, v127
	v_mov_b32_e32 v91, v127
	v_mov_b32_e32 v90, v127
	v_mov_b32_e32 v89, v127
	v_mov_b32_e32 v88, v127
	v_mov_b32_e32 v79, v127
	v_mov_b32_e32 v78, v127
	v_mov_b32_e32 v77, v127
	v_mov_b32_e32 v76, v127
	v_mov_b32_e32 v75, v127
	v_mov_b32_e32 v74, v127
	v_mov_b32_e32 v73, v127
	v_mov_b32_e32 v72, v127
	v_mov_b32_e32 v119, v127
	v_mov_b32_e32 v118, v127
	v_mov_b32_e32 v117, v127
	v_mov_b32_e32 v116, v127
	v_mov_b32_e32 v115, v127
	v_mov_b32_e32 v114, v127
	v_mov_b32_e32 v113, v127
	v_mov_b32_e32 v112, v127
	v_mov_b32_e32 v103, v127
	v_mov_b32_e32 v102, v127
	v_mov_b32_e32 v101, v127
	v_mov_b32_e32 v100, v127
	v_mov_b32_e32 v99, v127
	v_mov_b32_e32 v98, v127
	v_mov_b32_e32 v97, v127
	v_mov_b32_e32 v96, v127
	v_mov_b32_e32 v87, v127
	v_mov_b32_e32 v86, v127
	v_mov_b32_e32 v85, v127
	v_mov_b32_e32 v84, v127
	v_mov_b32_e32 v83, v127
	v_mov_b32_e32 v82, v127
	v_mov_b32_e32 v81, v127
	v_mov_b32_e32 v80, v127
	v_mov_b32_e32 v71, v127
	v_mov_b32_e32 v70, v127
	v_mov_b32_e32 v69, v127
	v_mov_b32_e32 v68, v127
	v_mov_b32_e32 v67, v127
	v_mov_b32_e32 v66, v127
	v_mov_b32_e32 v65, v127
	v_mov_b32_e32 v64, v127
	v_mov_b32_e32 v63, v127
	v_mov_b32_e32 v62, v127
	v_mov_b32_e32 v61, v127
	v_mov_b32_e32 v60, v127
	v_mov_b32_e32 v59, v127
	v_mov_b32_e32 v58, v127
	v_mov_b32_e32 v57, v127
	v_mov_b32_e32 v56, v127
	v_mov_b32_e32 v47, v127
	v_mov_b32_e32 v46, v127
	v_mov_b32_e32 v45, v127
	v_mov_b32_e32 v44, v127
	v_mov_b32_e32 v43, v127
	v_mov_b32_e32 v42, v127
	v_mov_b32_e32 v41, v127
	v_mov_b32_e32 v40, v127
	v_mov_b32_e32 v31, v127
	v_mov_b32_e32 v30, v127
	v_mov_b32_e32 v29, v127
	v_mov_b32_e32 v28, v127
	v_mov_b32_e32 v27, v127
	v_mov_b32_e32 v26, v127
	v_mov_b32_e32 v25, v127
	v_mov_b32_e32 v24, v127
	v_mov_b32_e32 v15, v127
	v_mov_b32_e32 v14, v127
	v_mov_b32_e32 v13, v127
	v_mov_b32_e32 v12, v127
	v_mov_b32_e32 v11, v127
	v_mov_b32_e32 v10, v127
	v_mov_b32_e32 v9, v127
	v_mov_b32_e32 v8, v127
	v_mov_b32_e32 v55, v127
	v_mov_b32_e32 v54, v127
	v_mov_b32_e32 v53, v127
	v_mov_b32_e32 v52, v127
	v_mov_b32_e32 v51, v127
	v_mov_b32_e32 v50, v127
	v_mov_b32_e32 v49, v127
	v_mov_b32_e32 v48, v127
	v_mov_b32_e32 v39, v127
	v_mov_b32_e32 v38, v127
	v_mov_b32_e32 v37, v127
	v_mov_b32_e32 v36, v127
	v_mov_b32_e32 v35, v127
	v_mov_b32_e32 v34, v127
	v_mov_b32_e32 v33, v127
	v_mov_b32_e32 v32, v127
	v_mov_b32_e32 v23, v127
	v_mov_b32_e32 v22, v127
	v_mov_b32_e32 v21, v127
	v_mov_b32_e32 v20, v127
	v_mov_b32_e32 v19, v127
	v_mov_b32_e32 v18, v127
	v_mov_b32_e32 v17, v127
	v_mov_b32_e32 v16, v127
	v_mov_b32_e32 v7, v127
	v_mov_b32_e32 v6, v127
	v_mov_b32_e32 v5, v127
	v_mov_b32_e32 v4, v127
	v_mov_b32_e32 v3, v127
	v_mov_b32_e32 v2, v127
	s_waitcnt lgkmcnt(0)
	v_mov_b32_e32 v1, v127
	v_mov_b32_e32 v0, v127
	s_cbranch_vccnz .LBB0_120
	s_add_u32 s39, s14, 0x100
	s_addc_u32 s40, s15, 0
	s_add_u32 s14, s16, 0x80
	s_addc_u32 s15, s17, 0
	s_mov_b32 s16, 0
	s_mov_b64 s[44:45], 0x80
	v_add_u32_e32 v224, 0x10000, v245
	v_add_u32_e32 v225, 0x14000, v245
	v_add_u32_e32 v226, 0x18000, v245
	v_add_u32_e32 v227, 0x1c000, v245
	s_add_i32 s86, s23, 0x10000
	s_add_i32 s87, s23, 0x14000
	s_add_i32 s88, s23, 0x18000
	s_add_i32 s89, s23, 0x1c000

; template <class Epi>
; __device__ __forceinline__ void gemm_phase(LAS unsigned char* lds, const Gemm g, const StaticOrder& S, const Epi& E) {
;     ...
;     f32x4 acc[2][2][4][2];
; #pragma unroll
;     for (int a = 0; a < 2; ++a)
; #pragma unroll
;         for (int b = 0; b < 2; ++b)
; #pragma unroll
;             for (int m = 0; m < 4; ++m)
; #pragma unroll
;                 for (int n = 0; n < 2; ++n) acc[a][b][m][n] = (f32x4){0.f, 0.f, 0.f, 0.f};
;     ...
;     for (;;) {
;         const bool has_next = S.next(ui + 1, nxt);
;         const char* nA = has_next ? (const char*)g.A + (size_t)nxt.pm * tstep : cA; const char* nB = has_next ? (const char*)g.Bt + (size_t)nxt.pn * tstep : cB;
;         for (int t = 0; t < nt; t += 2) {
;             const bool last = (t == nt - 2);
;             const char* a1 = cA + (size_t)(t + 1) * kstep;
;             const char* a2 = last ? nA : cA + (size_t)(t + 2) * kstep; const char* b2 = last ? nB : cB + (size_t)(t + 2) * kstep;
;             const char* a3 = a2 + kstep; const char* b3 = b2 + kstep;
.LBB0_163:
	v_mov_b32_e32 v127, 0
	s_andn2_b64 vcc, exec, s[6:7]
	v_mov_b32_e32 v126, v127
	v_mov_b32_e32 v125, v127
	v_mov_b32_e32 v124, v127
	v_mov_b32_e32 v123, v127
	v_mov_b32_e32 v122, v127
	v_mov_b32_e32 v121, v127
	v_mov_b32_e32 v120, v127
	v_mov_b32_e32 v111, v127
	v_mov_b32_e32 v110, v127
	v_mov_b32_e32 v109, v127
	v_mov_b32_e32 v108, v127
	v_mov_b32_e32 v107, v127
	v_mov_b32_e32 v106, v127
	v_mov_b32_e32 v105, v127
	v_mov_b32_e32 v104, v127
	v_mov_b32_e32 v95, v127
	v_mov_b32_e32 v94, v127
	v_mov_b32_e32 v93, v127
	v_mov_b32_e32 v92, v127
	v_mov_b32_e32 v91, v127
	v_mov_b32_e32 v90, v127
	v_mov_b32_e32 v89, v127
	v_mov_b32_e32 v88, v127
	v_mov_b32_e32 v79, v127
	v_mov_b32_e32 v78, v127
	v_mov_b32_e32 v77, v127
	v_mov_b32_e32 v76, v127
	v_mov_b32_e32 v75, v127
	v_mov_b32_e32 v74, v127
	v_mov_b32_e32 v73, v127
	v_mov_b32_e32 v72, v127
	v_mov_b32_e32 v119, v127
	v_mov_b32_e32 v118, v127
	v_mov_b32_e32 v117, v127
	v_mov_b32_e32 v116, v127
	v_mov_b32_e32 v115, v127
	v_mov_b32_e32 v114, v127
	v_mov_b32_e32 v113, v127
	v_mov_b32_e32 v112, v127
	v_mov_b32_e32 v103, v127
	v_mov_b32_e32 v102, v127
	v_mov_b32_e32 v101, v127
	v_mov_b32_e32 v100, v127
	v_mov_b32_e32 v99, v127
	v_mov_b32_e32 v98, v127
	v_mov_b32_e32 v97, v127
	v_mov_b32_e32 v96, v127
	v_mov_b32_e32 v87, v127
	v_mov_b32_e32 v86, v127
	v_mov_b32_e32 v85, v127
	v_mov_b32_e32 v84, v127
	v_mov_b32_e32 v83, v127
	v_mov_b32_e32 v82, v127
	v_mov_b32_e32 v81, v127
	v_mov_b32_e32 v80, v127
	v_mov_b32_e32 v71, v127
	v_mov_b32_e32 v70, v127
	v_mov_b32_e32 v69, v127
	v_mov_b32_e32 v68, v127
	v_mov_b32_e32 v67, v127
	v_mov_b32_e32 v66, v127
	v_mov_b32_e32 v65, v127
	v_mov_b32_e32 v64, v127
	v_mov_b32_e32 v63, v127
	v_mov_b32_e32 v62, v127
	v_mov_b32_e32 v61, v127
	v_mov_b32_e32 v60, v127
	v_mov_b32_e32 v59, v127
	v_mov_b32_e32 v58, v127
	v_mov_b32_e32 v57, v127
	v_mov_b32_e32 v56, v127
	v_mov_b32_e32 v47, v127
	v_mov_b32_e32 v46, v127
	v_mov_b32_e32 v45, v127
	v_mov_b32_e32 v44, v127
	v_mov_b32_e32 v43, v127
	v_mov_b32_e32 v42, v127
	v_mov_b32_e32 v41, v127
	v_mov_b32_e32 v40, v127
	v_mov_b32_e32 v31, v127
	v_mov_b32_e32 v30, v127
	v_mov_b32_e32 v29, v127
	v_mov_b32_e32 v28, v127
	v_mov_b32_e32 v27, v127
	v_mov_b32_e32 v26, v127
	v_mov_b32_e32 v25, v127
	v_mov_b32_e32 v24, v127
	v_mov_b32_e32 v15, v127
	v_mov_b32_e32 v14, v127
	v_mov_b32_e32 v13, v127
	v_mov_b32_e32 v12, v127
	v_mov_b32_e32 v11, v127
	v_mov_b32_e32 v10, v127
	v_mov_b32_e32 v9, v127
	v_mov_b32_e32 v8, v127
	v_mov_b32_e32 v55, v127
	v_mov_b32_e32 v54, v127
	v_mov_b32_e32 v53, v127
	v_mov_b32_e32 v52, v127
	v_mov_b32_e32 v51, v127
	v_mov_b32_e32 v50, v127
	v_mov_b32_e32 v49, v127
	v_mov_b32_e32 v48, v127
	v_mov_b32_e32 v39, v127
	v_mov_b32_e32 v38, v127
	v_mov_b32_e32 v37, v127
	v_mov_b32_e32 v36, v127
	v_mov_b32_e32 v35, v127
	v_mov_b32_e32 v34, v127
	v_mov_b32_e32 v33, v127
	v_mov_b32_e32 v32, v127
	v_mov_b32_e32 v23, v127
	v_mov_b32_e32 v22, v127
	v_mov_b32_e32 v21, v127
	v_mov_b32_e32 v20, v127
	v_mov_b32_e32 v19, v127
	v_mov_b32_e32 v18, v127
	v_mov_b32_e32 v17, v127
	v_mov_b32_e32 v16, v127
	v_mov_b32_e32 v7, v127
	v_mov_b32_e32 v6, v127
	v_mov_b32_e32 v5, v127
	v_mov_b32_e32 v4, v127
	v_mov_b32_e32 v3, v127
	v_mov_b32_e32 v2, v127
	v_mov_b32_e32 v1, v127
	v_mov_b32_e32 v0, v127
	s_cbranch_vccnz .LBB0_166
	s_add_u32 s42, s18, 0x100
	s_addc_u32 s43, s19, 0
	s_add_u32 s16, s16, 0x80
	s_addc_u32 s17, s17, 0
	s_mov_b32 s18, 0
	s_mov_b64 s[48:49], 0x80
	v_add_u32_e32 v224, 0x10000, v146
	v_add_u32_e32 v225, 0x14000, v146
	v_add_u32_e32 v226, 0x18000, v146
	v_add_u32_e32 v227, 0x1c000, v146
	s_add_i32 s86, s26, 0x10000
	s_add_i32 s87, s26, 0x14000
	s_add_i32 s88, s26, 0x18000
	s_add_i32 s89, s26, 0x1c000

; template <class Epi>
; __device__ __forceinline__ void gemm_phase(LAS unsigned char* lds, const Gemm g, const StaticOrder& S, const Epi& E) {
;     ...
;     f32x4 acc[2][2][4][2];
; #pragma unroll
;     for (int a = 0; a < 2; ++a)
; #pragma unroll
;         for (int b = 0; b < 2; ++b)
; #pragma unroll
;             for (int m = 0; m < 4; ++m)
; #pragma unroll
;                 for (int n = 0; n < 2; ++n) acc[a][b][m][n] = (f32x4){0.f, 0.f, 0.f, 0.f};
;     ...
;     for (;;) {
;         const bool has_next = S.next(ui + 1, nxt);
;         const char* nA = has_next ? (const char*)g.A + (size_t)nxt.pm * tstep : cA; const char* nB = has_next ? (const char*)g.Bt + (size_t)nxt.pn * tstep : cB;
;         for (int t = 0; t < nt; t += 2) {
;             const bool last = (t == nt - 2);
;             const char* a1 = cA + (size_t)(t + 1) * kstep;
;             const char* a2 = last ? nA : cA + (size_t)(t + 2) * kstep; const char* b2 = last ? nB : cB + (size_t)(t + 2) * kstep;
;             const char* a3 = a2 + kstep; const char* b3 = b2 + kstep;
.LBB0_526:
	v_mov_b32_e32 v127, 0
	s_andn2_b64 vcc, exec, s[6:7]
	v_mov_b32_e32 v126, v127
	v_mov_b32_e32 v125, v127
	v_mov_b32_e32 v124, v127
	v_mov_b32_e32 v123, v127
	v_mov_b32_e32 v122, v127
	v_mov_b32_e32 v121, v127
	v_mov_b32_e32 v120, v127
	v_mov_b32_e32 v111, v127
	v_mov_b32_e32 v110, v127
	v_mov_b32_e32 v109, v127
	v_mov_b32_e32 v108, v127
	v_mov_b32_e32 v107, v127
	v_mov_b32_e32 v106, v127
	v_mov_b32_e32 v105, v127
	v_mov_b32_e32 v104, v127
	v_mov_b32_e32 v95, v127
	v_mov_b32_e32 v94, v127
	v_mov_b32_e32 v93, v127
	v_mov_b32_e32 v92, v127
	v_mov_b32_e32 v91, v127
	v_mov_b32_e32 v90, v127
	v_mov_b32_e32 v89, v127
	v_mov_b32_e32 v88, v127
	v_mov_b32_e32 v79, v127
	v_mov_b32_e32 v78, v127
	v_mov_b32_e32 v77, v127
	v_mov_b32_e32 v76, v127
	v_mov_b32_e32 v75, v127
	v_mov_b32_e32 v74, v127
	v_mov_b32_e32 v73, v127
	v_mov_b32_e32 v72, v127
	v_mov_b32_e32 v119, v127
	v_mov_b32_e32 v118, v127
	v_mov_b32_e32 v117, v127
	v_mov_b32_e32 v116, v127
	v_mov_b32_e32 v115, v127
	v_mov_b32_e32 v114, v127
	v_mov_b32_e32 v113, v127
	v_mov_b32_e32 v112, v127
	v_mov_b32_e32 v103, v127
	v_mov_b32_e32 v102, v127
	v_mov_b32_e32 v101, v127
	v_mov_b32_e32 v100, v127
	v_mov_b32_e32 v99, v127
	v_mov_b32_e32 v98, v127
	v_mov_b32_e32 v97, v127
	v_mov_b32_e32 v96, v127
	v_mov_b32_e32 v87, v127
	v_mov_b32_e32 v86, v127
	v_mov_b32_e32 v85, v127
	v_mov_b32_e32 v84, v127
	v_mov_b32_e32 v83, v127
	v_mov_b32_e32 v82, v127
	v_mov_b32_e32 v81, v127
	v_mov_b32_e32 v80, v127
	v_mov_b32_e32 v71, v127
	v_mov_b32_e32 v70, v127
	v_mov_b32_e32 v69, v127
	v_mov_b32_e32 v68, v127
	v_mov_b32_e32 v67, v127
	v_mov_b32_e32 v66, v127
	v_mov_b32_e32 v65, v127
	v_mov_b32_e32 v64, v127
	v_mov_b32_e32 v63, v127
	v_mov_b32_e32 v62, v127
	v_mov_b32_e32 v61, v127
	v_mov_b32_e32 v60, v127
	v_mov_b32_e32 v59, v127
	v_mov_b32_e32 v58, v127
	v_mov_b32_e32 v57, v127
	v_mov_b32_e32 v56, v127
	v_mov_b32_e32 v47, v127
	v_mov_b32_e32 v46, v127
	v_mov_b32_e32 v45, v127
	v_mov_b32_e32 v44, v127
	v_mov_b32_e32 v43, v127
	v_mov_b32_e32 v42, v127
	v_mov_b32_e32 v41, v127
	v_mov_b32_e32 v40, v127
	v_mov_b32_e32 v31, v127
	v_mov_b32_e32 v30, v127
	v_mov_b32_e32 v29, v127
	v_mov_b32_e32 v28, v127
	v_mov_b32_e32 v27, v127
	v_mov_b32_e32 v26, v127
	v_mov_b32_e32 v25, v127
	v_mov_b32_e32 v24, v127
	v_mov_b32_e32 v15, v127
	v_mov_b32_e32 v14, v127
	v_mov_b32_e32 v13, v127
	v_mov_b32_e32 v12, v127
	v_mov_b32_e32 v11, v127
	v_mov_b32_e32 v10, v127
	v_mov_b32_e32 v9, v127
	v_mov_b32_e32 v8, v127
	v_mov_b32_e32 v55, v127
	v_mov_b32_e32 v54, v127
	v_mov_b32_e32 v53, v127
	v_mov_b32_e32 v52, v127
	v_mov_b32_e32 v51, v127
	v_mov_b32_e32 v50, v127
	v_mov_b32_e32 v49, v127
	v_mov_b32_e32 v48, v127
	v_mov_b32_e32 v39, v127
	v_mov_b32_e32 v38, v127
	v_mov_b32_e32 v37, v127
	v_mov_b32_e32 v36, v127
	v_mov_b32_e32 v35, v127
	v_mov_b32_e32 v34, v127
	v_mov_b32_e32 v33, v127
	v_mov_b32_e32 v32, v127
	v_mov_b32_e32 v23, v127
	v_mov_b32_e32 v22, v127
	v_mov_b32_e32 v21, v127
	v_mov_b32_e32 v20, v127
	v_mov_b32_e32 v19, v127
	v_mov_b32_e32 v18, v127
	v_mov_b32_e32 v17, v127
	v_mov_b32_e32 v16, v127
	v_mov_b32_e32 v7, v127
	v_mov_b32_e32 v6, v127
	v_mov_b32_e32 v5, v127
	v_mov_b32_e32 v4, v127
	v_mov_b32_e32 v3, v127
	v_mov_b32_e32 v2, v127
	v_mov_b32_e32 v1, v127
	v_mov_b32_e32 v0, v127
	s_cbranch_vccnz .LBB0_529
	s_add_u32 s40, s18, 0x100
	s_addc_u32 s41, s19, 0
	s_add_u32 s16, s16, 0x80
	s_addc_u32 s17, s17, 0
	s_mov_b32 s18, 0
	s_mov_b64 s[46:47], 0x80
	v_add_u32_e32 v224, 0x10000, v144
	v_add_u32_e32 v225, 0x14000, v144
	v_add_u32_e32 v226, 0x18000, v144
	v_add_u32_e32 v227, 0x1c000, v144
	s_add_i32 s86, s24, 0x10000
	s_add_i32 s87, s24, 0x14000
	s_add_i32 s88, s24, 0x18000
	s_add_i32 s89, s24, 0x1c000
